# ssm pass-3: all chunk loads (rstd rows, u rows for both halves) issued at the chunk top behind one wait; scan loop rewritten with scalar f32 ops and precomputed swizzled LDS addresses (arithmetic orde
# speedup vs baseline: 1.0040x; 1.0032x over previous
; template <int PASS> __device__ __forceinline__ void ssm_phase(int j, LAS unsigned char* lds, int lane, int wave) { KARGS;
;     ...
;             { const int t = 64 * c + lane; float ssq = 0.f;
; #pragma unroll
;               for (int q = 0; q < 8; ++q) { const f32x4 v = *(const f32x4*)(rsp + (size_t)t * 64 + 4 * q); ssq += (v[0] + v[1]) + (v[2] + v[3]); }
;               rsL[lane] = rsqrtf(ssq * (1.0f / D) + EPS); }
;     ...
;                     if (fq < 2) { const int l = 32 * half + 16 * lt + fr; const float rs = rsL[l]; const float* xp = X + (size_t)(64 * c + l) * D + 16 * g + 8 * fq;
;                         const f32x4 x0 = *(const f32x4*)xp * rs, x1 = *(const f32x4*)(xp + 4) * rs;
.LBB0_342:
	s_lshl_b32 s12, s53, 6
	v_or_b32_e32 v52, s12, v60
	v_ashrrev_i32_e32 v53, 31, v52
	v_lshlrev_b64 v[52:53], 8, v[52:53]
	v_lshl_add_u64 v[106:107], s[62:63], 0, v[52:53]
	global_load_dwordx4 v[52:55], v[106:107], off offset:48
	global_load_dwordx4 v[56:59], v[106:107], off offset:32
	global_load_dwordx4 v[98:101], v[106:107], off
	global_load_dwordx4 v[102:105], v[106:107], off offset:16
	s_or_b32 s13, s12, 16
	s_or_b32 s54, s12, 1
	s_or_b32 s55, s12, 2
	s_or_b32 s68, s12, 3
	s_or_b32 s77, s12, 17
	s_or_b32 s80, s12, 18
	s_or_b32 s81, s12, 19
	s_mov_b32 s70, 0
	s_mov_b64 s[4:5], -1
	global_load_dwordx4 v[140:143], v[106:107], off offset:112
	global_load_dwordx4 v[144:147], v[106:107], off offset:96
	global_load_dwordx4 v[148:151], v[106:107], off offset:80
	global_load_dwordx4 v[152:155], v[106:107], off offset:64
	v_add_u32_e32 v211, s15, v77
	v_xor_b32_e32 v195, 0, v63
	v_lshlrev_b32_e32 v195, 4, v195
	v_add3_u32 v195, s15, v195, v73
	v_xor_b32_e32 v196, 1, v63
	v_lshlrev_b32_e32 v196, 4, v196
	v_add3_u32 v196, s15, v196, v73
	v_xor_b32_e32 v197, 2, v63
	v_lshlrev_b32_e32 v197, 4, v197
	v_add3_u32 v197, s15, v197, v73
	v_xor_b32_e32 v198, 3, v63
	v_lshlrev_b32_e32 v198, 4, v198
	v_add3_u32 v198, s15, v198, v73
	v_xor_b32_e32 v199, 4, v63
	v_lshlrev_b32_e32 v199, 4, v199
	v_add3_u32 v199, s15, v199, v73
	v_xor_b32_e32 v200, 5, v63
	v_lshlrev_b32_e32 v200, 4, v200
	v_add3_u32 v200, s15, v200, v73
	v_xor_b32_e32 v201, 6, v63
	v_lshlrev_b32_e32 v201, 4, v201
	v_add3_u32 v201, s15, v201, v73
	v_xor_b32_e32 v202, 7, v63
	v_lshlrev_b32_e32 v202, 4, v202
	v_add3_u32 v202, s15, v202, v73
	v_xor_b32_e32 v203, 8, v63
	v_lshlrev_b32_e32 v203, 4, v203
	v_add3_u32 v203, s15, v203, v73
	v_xor_b32_e32 v204, 9, v63
	v_lshlrev_b32_e32 v204, 4, v204
	v_add3_u32 v204, s15, v204, v73
	v_xor_b32_e32 v205, 10, v63
	v_lshlrev_b32_e32 v205, 4, v205
	v_add3_u32 v205, s15, v205, v73
	v_xor_b32_e32 v206, 11, v63
	v_lshlrev_b32_e32 v206, 4, v206
	v_add3_u32 v206, s15, v206, v73
	v_xor_b32_e32 v207, 12, v63
	v_lshlrev_b32_e32 v207, 4, v207
	v_add3_u32 v207, s15, v207, v73
	v_xor_b32_e32 v208, 13, v63
	v_lshlrev_b32_e32 v208, 4, v208
	v_add3_u32 v208, s15, v208, v73
	v_xor_b32_e32 v209, 14, v63
	v_lshlrev_b32_e32 v209, 4, v209
	v_add3_u32 v209, s15, v209, v73
	v_xor_b32_e32 v210, 15, v63
	v_lshlrev_b32_e32 v210, 4, v210
	v_add3_u32 v210, s15, v210, v73
	s_and_saveexec_b64 s[100:101], s[8:9]
	v_mov_b32_e32 v188, v62
	v_or_b32_e32 v188, s12, v188
	v_ashrrev_i32_e32 v189, 31, v188
	v_lshlrev_b64 v[188:189], 13, v[188:189]
	v_lshl_add_u64 v[188:189], v[88:89], 0, v[188:189]
	global_load_dwordx4 v[156:159], v[188:189], off
	global_load_dwordx4 v[160:163], v[188:189], off offset:16
	v_mov_b32_e32 v190, v62
	v_or_b32_e32 v190, s13, v190
	v_ashrrev_i32_e32 v191, 31, v190
	v_lshlrev_b64 v[190:191], 13, v[190:191]
	v_lshl_add_u64 v[190:191], v[88:89], 0, v[190:191]
	global_load_dwordx4 v[164:167], v[190:191], off
	global_load_dwordx4 v[168:171], v[190:191], off offset:16
	v_or_b32_e32 v188, 32, v62
	v_or_b32_e32 v188, s12, v188
	v_ashrrev_i32_e32 v189, 31, v188
	v_lshlrev_b64 v[188:189], 13, v[188:189]
	v_lshl_add_u64 v[188:189], v[88:89], 0, v[188:189]
	global_load_dwordx4 v[172:175], v[188:189], off
	global_load_dwordx4 v[176:179], v[188:189], off offset:16
	v_or_b32_e32 v190, 32, v62
	v_or_b32_e32 v190, s13, v190
	v_ashrrev_i32_e32 v191, 31, v190
	v_lshlrev_b64 v[190:191], 13, v[190:191]
	v_lshl_add_u64 v[190:191], v[88:89], 0, v[190:191]
	global_load_dwordx4 v[180:183], v[190:191], off
	global_load_dwordx4 v[184:187], v[190:191], off offset:16
	s_mov_b64 exec, s[100:101]
	s_waitcnt vmcnt(0)
	v_add_f32_e32 v112, v52, v53
	v_add_f32_e32 v114, v54, v55
	v_mov_b32_e32 v108, v98
	v_mov_b32_e32 v109, v102
	v_mov_b32_e32 v102, v99
	v_pk_add_f32 v[98:99], v[108:109], v[102:103]
	v_mov_b32_e32 v102, v100
	v_mov_b32_e32 v103, v104
	v_mov_b32_e32 v104, v101
	v_pk_add_f32 v[100:101], v[102:103], v[104:105]
	s_nop 0
	v_pk_add_f32 v[98:99], v[98:99], v[100:101]
	s_nop 0
	v_add_f32_e32 v97, 0, v98
	v_add_f32_e32 v108, v97, v99
	v_mov_b32_e32 v98, v57
	v_mov_b32_e32 v99, v58
	v_mov_b32_e32 v57, v59
	v_pk_add_f32 v[56:57], v[98:99], v[56:57]
	s_nop 0
	v_pk_add_f32 v[110:111], v[56:57], v[56:57] op_sel:[0,1] op_sel_hi:[1,0]
	v_mov_b64_e32 v[52:53], v[140:141]
	v_mov_b64_e32 v[54:55], v[142:143]
	v_mov_b64_e32 v[56:57], v[144:145]
	v_mov_b64_e32 v[58:59], v[146:147]
	v_mov_b64_e32 v[98:99], v[148:149]
	v_mov_b64_e32 v[100:101], v[150:151]
	v_mov_b64_e32 v[102:103], v[152:153]
	v_mov_b64_e32 v[104:105], v[154:155]
	v_add_f32_e32 v56, v56, v57
	v_add_f32_e32 v58, v58, v59
	v_mov_b32_e32 v109, v102
	v_mov_b32_e32 v111, v103
	v_mov_b32_e32 v113, v104
	v_mov_b32_e32 v115, v105
	v_pk_add_f32 v[102:103], v[108:109], v[110:111]
	v_pk_add_f32 v[104:105], v[112:113], v[114:115]
	v_mov_b32_e32 v57, v54
	v_pk_add_f32 v[102:103], v[102:103], v[104:105]
	v_mov_b32_e32 v104, v99
	v_mov_b32_e32 v105, v100
	v_mov_b32_e32 v99, v101
	v_pk_add_f32 v[98:99], v[104:105], v[98:99]
	v_pk_add_f32 v[102:103], v[102:103], v[102:103] op_sel:[0,1] op_sel_hi:[1,0]
	v_pk_add_f32 v[98:99], v[98:99], v[98:99] op_sel:[0,1] op_sel_hi:[1,0]
	v_mov_b32_e32 v103, v52
	v_mov_b32_e32 v99, v53
	v_mov_b32_e32 v59, v55
	v_pk_add_f32 v[52:53], v[102:103], v[98:99]
	v_pk_add_f32 v[54:55], v[56:57], v[58:59]
	s_nop 0
	v_pk_add_f32 v[52:53], v[52:53], v[54:55]
	s_nop 0
	v_add_f32_e32 v52, v52, v53
	v_fmamk_f32 v52, v52, 0x3a000000, v223
	v_cmp_gt_f32_e32 vcc, s97, v52
	v_mul_f32_e32 v53, 0x4b800000, v52
	s_nop 0
	v_cndmask_b32_e32 v52, v52, v53, vcc
	v_rsq_f32_e32 v52, v52
	s_nop 0
	v_mul_f32_e32 v53, 0x45800000, v52
	v_cndmask_b32_e32 v52, v52, v53, vcc
	ds_write_b32 v81, v52 offset:16384
	s_waitcnt lgkmcnt(0)
; #define LAS __attribute__((address_space(3)))
; __device__ __forceinline__ unsigned pk2(float lo, float hi) { const f32x2 v = {lo, hi}; const bf16x2_t b = __builtin_convertvector(v, bf16x2_t); return __builtin_bit_cast(unsigned, b); }
; template <int PASS> __device__ __forceinline__ void ssm_phase(int j, LAS unsigned char* lds, int lane, int wave) { KARGS;
;     ...
;                 for (int lt = 0; lt < 2; ++lt) {
;                     bf16x8 uf = {0, 0, 0, 0, 0, 0, 0, 0};
;                     if (fq < 2) { const int l = 32 * half + 16 * lt + fr; const float rs = rsL[l]; const float* xp = X + (size_t)(64 * c + l) * D + 16 * g + 8 * fq;
;                         const f32x4 x0 = *(const f32x4*)xp * rs, x1 = *(const f32x4*)(xp + 4) * rs;
;                         u32x4 w; w.x = pk2(x0[0], x0[1]); w.y = pk2(x0[2], x0[3]); w.z = pk2(x1[0], x1[1]); w.w = pk2(x1[2], x1[3]); uf = __builtin_bit_cast(bf16x8, w); }
;                     f32x4 dre[4], dim[4];
; #pragma unroll
;                     for (int pt = 0; pt < 4; ++pt) { const f32x4 z4 = {0.f, 0.f, 0.f, 0.f};
;                         dre[pt] = __builtin_amdgcn_mfma_f32_16x16x32_bf16(uf, bfr[pt], z4, 0, 0, 0); dim[pt] = __builtin_amdgcn_mfma_f32_16x16x32_bf16(uf, bfi[pt], z4, 0, 0, 0); }
;                     asm volatile("s_nop 15\n\ts_nop 15" : "+v"(dre[0]), "+v"(dre[1]), "+v"(dre[2]), "+v"(dre[3]), "+v"(dim[0]), "+v"(dim[1]), "+v"(dim[2]), "+v"(dim[3]));
; #pragma unroll
;                     for (int pt = 0; pt < 4; ++pt)
; #pragma unroll
;                         for (int r = 0; r < 4; ++r) *(LAS unsigned*)(buL + (16 * lt + 4 * fq + r) * 256 + 4 * (16 * pt + fr)) = pk2(dre[pt][r], dim[pt][r]);
.LBB0_343:
	v_or_b32_e32 v134, s70, v72
	v_or_b32_e32 v136, s12, v134
	v_ashrrev_i32_e32 v137, 31, v136
	v_lshlrev_b64 v[136:137], 11, v[136:137]
	v_or_b32_e32 v136, v136, v86
	v_lshl_add_u64 v[136:137], v[136:137], 2, s[60:61]
	global_load_dword v126, v[136:137], off
	v_or_b32_e32 v138, s54, v134
	v_ashrrev_i32_e32 v139, 31, v138
	v_lshlrev_b64 v[138:139], 11, v[138:139]
	v_or_b32_e32 v138, v138, v86
	v_lshl_add_u64 v[138:139], v[138:139], 2, s[60:61]
	global_load_dword v127, v[138:139], off
	v_or_b32_e32 v136, s55, v134
	v_ashrrev_i32_e32 v137, 31, v136
	v_lshlrev_b64 v[136:137], 11, v[136:137]
	v_or_b32_e32 v136, v136, v86
	v_lshl_add_u64 v[136:137], v[136:137], 2, s[60:61]
	global_load_dword v128, v[136:137], off
	v_or_b32_e32 v138, s68, v134
	v_ashrrev_i32_e32 v139, 31, v138
	v_lshlrev_b64 v[138:139], 11, v[138:139]
	v_or_b32_e32 v138, v138, v86
	v_lshl_add_u64 v[138:139], v[138:139], 2, s[60:61]
	global_load_dword v129, v[138:139], off
	v_or_b32_e32 v136, s13, v134
	v_ashrrev_i32_e32 v137, 31, v136
	v_lshlrev_b64 v[136:137], 11, v[136:137]
	v_or_b32_e32 v136, v136, v86
	v_lshl_add_u64 v[136:137], v[136:137], 2, s[60:61]
	global_load_dword v130, v[136:137], off
	v_or_b32_e32 v138, s77, v134
	v_ashrrev_i32_e32 v139, 31, v138
	v_lshlrev_b64 v[138:139], 11, v[138:139]
	v_or_b32_e32 v138, v138, v86
	v_lshl_add_u64 v[138:139], v[138:139], 2, s[60:61]
	global_load_dword v131, v[138:139], off
	v_or_b32_e32 v136, s80, v134
	v_ashrrev_i32_e32 v137, 31, v136
	v_lshlrev_b64 v[136:137], 11, v[136:137]
	v_or_b32_e32 v136, v136, v86
	v_lshl_add_u64 v[136:137], v[136:137], 2, s[60:61]
	global_load_dword v132, v[136:137], off
	v_or_b32_e32 v138, s81, v134
	v_ashrrev_i32_e32 v139, 31, v138
	v_lshlrev_b64 v[138:139], 11, v[138:139]
	v_or_b32_e32 v138, v138, v86
	v_lshl_add_u64 v[138:139], v[138:139], 2, s[60:61]
	global_load_dword v133, v[138:139], off
	v_or_b32_e32 v59, s70, v62
	v_mov_b32_e32 v52, 0
	v_lshl_add_u32 v58, v59, 2, s18
	v_mov_b32_e32 v54, 0
	v_mov_b32_e32 v55, 0
	v_mov_b32_e32 v56, 0
	v_mov_b32_e32 v57, 0
	s_and_saveexec_b64 s[10:11], s[8:9]
	s_cbranch_execz .LBB0_345
	v_or_b32_e32 v54, s12, v59
	v_ashrrev_i32_e32 v55, 31, v54
	v_lshlrev_b64 v[54:55], 13, v[54:55]
	v_mov_b64_e32 v[54:55], v[156:157]
	v_mov_b64_e32 v[56:57], v[158:159]
	v_mov_b64_e32 v[98:99], v[160:161]
	v_mov_b64_e32 v[100:101], v[162:163]
	ds_read_b32 v102, v58 offset:16384
	s_waitcnt lgkmcnt(0)
	v_pk_mul_f32 v[56:57], v[56:57], v[102:103] op_sel_hi:[1,0]
	v_pk_mul_f32 v[54:55], v[54:55], v[102:103] op_sel_hi:[1,0]
	v_pk_mul_f32 v[100:101], v[100:101], v[102:103] op_sel_hi:[1,0]
	v_pk_mul_f32 v[98:99], v[98:99], v[102:103] op_sel_hi:[1,0]
	v_cvt_pk_bf16_f32 v54, v54, v55
	v_cvt_pk_bf16_f32 v55, v56, v57
	v_cvt_pk_bf16_f32 v56, v98, v99
	v_cvt_pk_bf16_f32 v57, v100, v101
.LBB0_345:
	s_or_b64 exec, exec, s[10:11]
	s_nop 0
	v_mfma_f32_16x16x32_bf16 v[98:101], v[54:57], v[12:15], 0
	v_mfma_f32_16x16x32_bf16 v[102:105], v[54:57], v[8:11], 0
	v_mfma_f32_16x16x32_bf16 v[106:109], v[54:57], v[16:19], 0
	v_mfma_f32_16x16x32_bf16 v[110:113], v[54:57], v[4:7], 0
	v_mfma_f32_16x16x32_bf16 v[114:117], v[54:57], v[28:31], 0
	v_mfma_f32_16x16x32_bf16 v[118:121], v[54:57], v[24:27], 0
	v_mfma_f32_16x16x32_bf16 v[122:125], v[54:57], v[32:35], 0
	v_mfma_f32_16x16x32_bf16 v[54:57], v[54:57], v[20:23], 0
	s_nop 15
	s_nop 15
	s_nop 1
	v_cvt_pk_bf16_f32 v53, v98, v102
	v_cvt_pk_bf16_f32 v97, v99, v103
	v_cvt_pk_bf16_f32 v98, v100, v104
	v_cvt_pk_bf16_f32 v99, v101, v105
	v_cvt_pk_bf16_f32 v100, v106, v110
	v_add_u32_e32 v101, 0x2000, v96
	ds_write2_b32 v101, v53, v100 offset1:16
	v_cvt_pk_bf16_f32 v53, v107, v111
	ds_write2_b32 v101, v97, v53 offset0:64 offset1:80
	v_cvt_pk_bf16_f32 v53, v108, v112
	ds_write2_b32 v101, v98, v53 offset0:128 offset1:144
	v_cvt_pk_bf16_f32 v53, v109, v113
	ds_write2_b32 v101, v99, v53 offset0:192 offset1:208
	v_cvt_pk_bf16_f32 v53, v114, v118
	v_cvt_pk_bf16_f32 v54, v122, v54
	v_cvt_pk_bf16_f32 v97, v115, v119
	ds_write2_b32 v101, v53, v54 offset0:32 offset1:48
	v_cvt_pk_bf16_f32 v53, v123, v55
	v_cvt_pk_bf16_f32 v98, v116, v120
	ds_write2_b32 v101, v97, v53 offset0:96 offset1:112
	v_cvt_pk_bf16_f32 v53, v124, v56
	v_cvt_pk_bf16_f32 v99, v117, v121
	ds_write2_b32 v101, v98, v53 offset0:160 offset1:176
	v_cvt_pk_bf16_f32 v53, v125, v57
	ds_write2_b32 v101, v99, v53 offset0:224 offset1:240
	v_mov_b32_e32 v53, 0
	v_mov_b32_e32 v54, 0
	v_mov_b32_e32 v55, 0
	s_and_saveexec_b64 s[10:11], s[8:9]
	s_cbranch_execz .LBB0_347
	v_or_b32_e32 v52, s13, v59
	v_ashrrev_i32_e32 v53, 31, v52
	v_lshlrev_b64 v[52:53], 13, v[52:53]
	v_mov_b64_e32 v[52:53], v[164:165]
	v_mov_b64_e32 v[54:55], v[166:167]
	v_mov_b64_e32 v[98:99], v[168:169]
	v_mov_b64_e32 v[100:101], v[170:171]
	ds_read_b32 v56, v58 offset:16448
	s_waitcnt lgkmcnt(0)
	v_pk_mul_f32 v[54:55], v[54:55], v[56:57] op_sel_hi:[1,0]
	v_pk_mul_f32 v[52:53], v[52:53], v[56:57] op_sel_hi:[1,0]
	v_pk_mul_f32 v[58:59], v[100:101], v[56:57] op_sel_hi:[1,0]
	v_pk_mul_f32 v[56:57], v[98:99], v[56:57] op_sel_hi:[1,0]
	v_cvt_pk_bf16_f32 v52, v52, v53
	v_cvt_pk_bf16_f32 v53, v54, v55
	v_cvt_pk_bf16_f32 v54, v56, v57
	v_cvt_pk_bf16_f32 v55, v58, v59
; #define LAS __attribute__((address_space(3)))
; __device__ __forceinline__ unsigned pk2(float lo, float hi) { const f32x2 v = {lo, hi}; const bf16x2_t b = __builtin_convertvector(v, bf16x2_t); return __builtin_bit_cast(unsigned, b); }
; #define CBAR() asm volatile("s_waitcnt lgkmcnt(0)" ::: "memory")
; template <int PASS> __device__ __forceinline__ void ssm_phase(int j, LAS unsigned char* lds, int lane, int wave) { KARGS;
;     ...
;                         dre[pt] = __builtin_amdgcn_mfma_f32_16x16x32_bf16(uf, bfr[pt], z4, 0, 0, 0); dim[pt] = __builtin_amdgcn_mfma_f32_16x16x32_bf16(uf, bfi[pt], z4, 0, 0, 0); }
;                     asm volatile("s_nop 15\n\ts_nop 15" : "+v"(dre[0]), "+v"(dre[1]), "+v"(dre[2]), "+v"(dre[3]), "+v"(dim[0]), "+v"(dim[1]), "+v"(dim[2]), "+v"(dim[3]));
; #pragma unroll
;                     for (int pt = 0; pt < 4; ++pt)
; #pragma unroll
;                         for (int r = 0; r < 4; ++r) *(LAS unsigned*)(buL + (16 * lt + 4 * fq + r) * 256 + 4 * (16 * pt + fr)) = pk2(dre[pt][r], dim[pt][r]);
;                 }
;                 CBAR();
; #pragma unroll 1
;                 for (int l8 = 0; l8 < 32; l8 += 8) {
;                     unsigned w[8];
; #pragma unroll
;                     for (int q = 0; q < 8; ++q) w[q] = *(const LAS unsigned*)(buL + (l8 + q) * 256 + 4 * p);
; #pragma unroll
;                     for (int q = 0; q < 8; ++q) {
;                         const float nr = abr * hr - abi * hi + bflo(w[q]), ni = abr * hi + abi * hr + bfhi(w[q]); hr = nr; hi = ni;
;                         if (PASS == 3) *(LAS unsigned*)(hL + (l8 + q) * 256 + ((((p >> 2) ^ ((l8 + q) & 15))) << 4) + (p & 3) * 4) = pk2(hr, hi);
;                     }
;                 }
.LBB0_347:
	s_or_b64 exec, exec, s[10:11]
	s_nop 0
	v_mfma_f32_16x16x32_bf16 v[56:59], v[52:55], v[12:15], 0
	s_xor_b64 s[10:11], s[4:5], -1
	s_mov_b32 s4, -8
	v_mfma_f32_16x16x32_bf16 v[98:101], v[52:55], v[8:11], 0
	v_mfma_f32_16x16x32_bf16 v[102:105], v[52:55], v[16:19], 0
	v_mfma_f32_16x16x32_bf16 v[106:109], v[52:55], v[4:7], 0
	v_mfma_f32_16x16x32_bf16 v[110:113], v[52:55], v[28:31], 0
	v_mfma_f32_16x16x32_bf16 v[114:117], v[52:55], v[24:27], 0
	v_mfma_f32_16x16x32_bf16 v[118:121], v[52:55], v[32:35], 0
	v_mfma_f32_16x16x32_bf16 v[52:55], v[52:55], v[20:23], 0
	s_nop 15
	s_nop 15
	s_nop 1
	v_cvt_pk_bf16_f32 v56, v56, v98
	s_nop 0
	v_cvt_pk_bf16_f32 v97, v102, v106
	v_add_u32_e32 v98, 0x3000, v96
	v_cvt_pk_bf16_f32 v57, v57, v99
	ds_write2_b32 v98, v56, v97 offset1:16
	v_cvt_pk_bf16_f32 v56, v103, v107
	v_cvt_pk_bf16_f32 v58, v58, v100
	ds_write2_b32 v98, v57, v56 offset0:64 offset1:80
	v_cvt_pk_bf16_f32 v56, v104, v108
	v_cvt_pk_bf16_f32 v59, v59, v101
	ds_write2_b32 v98, v58, v56 offset0:128 offset1:144
	v_cvt_pk_bf16_f32 v56, v105, v109
	ds_write2_b32 v98, v59, v56 offset0:192 offset1:208
	v_cvt_pk_bf16_f32 v56, v110, v114
	v_cvt_pk_bf16_f32 v52, v118, v52
	v_cvt_pk_bf16_f32 v57, v111, v115
	ds_write2_b32 v98, v56, v52 offset0:32 offset1:48
	v_cvt_pk_bf16_f32 v52, v119, v53
	v_cvt_pk_bf16_f32 v58, v112, v116
	ds_write2_b32 v98, v57, v52 offset0:96 offset1:112
	v_cvt_pk_bf16_f32 v52, v120, v54
	v_cvt_pk_bf16_f32 v59, v113, v117
	ds_write2_b32 v98, v58, v52 offset0:160 offset1:176
	v_cvt_pk_bf16_f32 v52, v121, v55
	ds_write2_b32 v98, v59, v52 offset0:224 offset1:240
	s_waitcnt lgkmcnt(0)
	ds_read2st64_b32 v[52:53], v211 offset0:0 offset1:1
	ds_read2st64_b32 v[54:55], v211 offset0:2 offset1:3
	ds_read2st64_b32 v[56:57], v211 offset0:4 offset1:5
	ds_read2st64_b32 v[58:59], v211 offset0:6 offset1:7
	s_waitcnt lgkmcnt(0)
	ds_read2st64_b32 v[98:99], v211 offset0:8 offset1:9
	ds_read2st64_b32 v[100:101], v211 offset0:10 offset1:11
	ds_read2st64_b32 v[102:103], v211 offset0:12 offset1:13
	ds_read2st64_b32 v[104:105], v211 offset0:14 offset1:15
	v_mul_f32_e32 v106, v84, v0
	v_mul_f32_e32 v107, v85, v1
	v_lshlrev_b32_e32 v108, 16, v52
	v_and_b32_e32 v109, 0xffff0000, v52
	v_fma_f32 v0, v2, v0, -v107
	v_fma_f32 v1, v3, v1, v106
	v_add_f32_e32 v0, v0, v108
	v_add_f32_e32 v1, v1, v109
	v_cvt_pk_bf16_f32 v110, v0, v1
	ds_write_b32 v195, v110
	v_mul_f32_e32 v111, v84, v0
	v_mul_f32_e32 v112, v85, v1
	v_lshlrev_b32_e32 v113, 16, v53
	v_and_b32_e32 v114, 0xffff0000, v53
	v_fma_f32 v0, v2, v0, -v112
	v_fma_f32 v1, v3, v1, v111
	v_add_f32_e32 v0, v0, v113
	v_add_f32_e32 v1, v1, v114
	v_cvt_pk_bf16_f32 v115, v0, v1
	ds_write_b32 v196, v115 offset:256
	v_mul_f32_e32 v106, v84, v0
	v_mul_f32_e32 v107, v85, v1
	v_lshlrev_b32_e32 v108, 16, v54
	v_and_b32_e32 v109, 0xffff0000, v54
	v_fma_f32 v0, v2, v0, -v107
	v_fma_f32 v1, v3, v1, v106
	v_add_f32_e32 v0, v0, v108
	v_add_f32_e32 v1, v1, v109
	v_cvt_pk_bf16_f32 v110, v0, v1
	ds_write_b32 v197, v110 offset:512
	v_mul_f32_e32 v111, v84, v0
	v_mul_f32_e32 v112, v85, v1
	v_lshlrev_b32_e32 v113, 16, v55
	v_and_b32_e32 v114, 0xffff0000, v55
	v_fma_f32 v0, v2, v0, -v112
	v_fma_f32 v1, v3, v1, v111
	v_add_f32_e32 v0, v0, v113
	v_add_f32_e32 v1, v1, v114
	v_cvt_pk_bf16_f32 v115, v0, v1
	ds_write_b32 v198, v115 offset:768
	v_mul_f32_e32 v106, v84, v0
	v_mul_f32_e32 v107, v85, v1
	v_lshlrev_b32_e32 v108, 16, v56
	v_and_b32_e32 v109, 0xffff0000, v56
	v_fma_f32 v0, v2, v0, -v107
	v_fma_f32 v1, v3, v1, v106
	v_add_f32_e32 v0, v0, v108
	v_add_f32_e32 v1, v1, v109
	v_cvt_pk_bf16_f32 v110, v0, v1
	ds_write_b32 v199, v110 offset:1024
	v_mul_f32_e32 v111, v84, v0
	v_mul_f32_e32 v112, v85, v1
	v_lshlrev_b32_e32 v113, 16, v57
	v_and_b32_e32 v114, 0xffff0000, v57
	v_fma_f32 v0, v2, v0, -v112
	v_fma_f32 v1, v3, v1, v111
	v_add_f32_e32 v0, v0, v113
	v_add_f32_e32 v1, v1, v114
	v_cvt_pk_bf16_f32 v115, v0, v1
	ds_write_b32 v200, v115 offset:1280
	v_mul_f32_e32 v106, v84, v0
	v_mul_f32_e32 v107, v85, v1
	v_lshlrev_b32_e32 v108, 16, v58
	v_and_b32_e32 v109, 0xffff0000, v58
	v_fma_f32 v0, v2, v0, -v107
	v_fma_f32 v1, v3, v1, v106
	v_add_f32_e32 v0, v0, v108
	v_add_f32_e32 v1, v1, v109
	v_cvt_pk_bf16_f32 v110, v0, v1
	ds_write_b32 v201, v110 offset:1536
	v_mul_f32_e32 v111, v84, v0
	v_mul_f32_e32 v112, v85, v1
	v_lshlrev_b32_e32 v113, 16, v59
	v_and_b32_e32 v114, 0xffff0000, v59
	v_fma_f32 v0, v2, v0, -v112
	v_fma_f32 v1, v3, v1, v111
	v_add_f32_e32 v0, v0, v113
	v_add_f32_e32 v1, v1, v114
	v_cvt_pk_bf16_f32 v115, v0, v1
	ds_write_b32 v202, v115 offset:1792
	s_waitcnt lgkmcnt(8)
; #define LAS __attribute__((address_space(3)))
; __device__ __forceinline__ unsigned pk2(float lo, float hi) { const f32x2 v = {lo, hi}; const bf16x2_t b = __builtin_convertvector(v, bf16x2_t); return __builtin_bit_cast(unsigned, b); }
; template <int PASS> __device__ __forceinline__ void ssm_phase(int j, LAS unsigned char* lds, int lane, int wave) { KARGS;
;     ...
;                 for (int l8 = 0; l8 < 32; l8 += 8) {
;                     unsigned w[8];
; #pragma unroll
;                     for (int q = 0; q < 8; ++q) w[q] = *(const LAS unsigned*)(buL + (l8 + q) * 256 + 4 * p);
; #pragma unroll
;                     for (int q = 0; q < 8; ++q) {
;                         const float nr = abr * hr - abi * hi + bflo(w[q]), ni = abr * hi + abi * hr + bfhi(w[q]); hr = nr; hi = ni;
;                         if (PASS == 3) *(LAS unsigned*)(hL + (l8 + q) * 256 + ((((p >> 2) ^ ((l8 + q) & 15))) << 4) + (p & 3) * 4) = pk2(hr, hi);
;                     }
;                 }
	ds_read2st64_b32 v[52:53], v211 offset0:16 offset1:17
	ds_read2st64_b32 v[54:55], v211 offset0:18 offset1:19
	ds_read2st64_b32 v[56:57], v211 offset0:20 offset1:21
	ds_read2st64_b32 v[58:59], v211 offset0:22 offset1:23
	v_mul_f32_e32 v106, v84, v0
	v_mul_f32_e32 v107, v85, v1
	v_lshlrev_b32_e32 v108, 16, v98
	v_and_b32_e32 v109, 0xffff0000, v98
	v_fma_f32 v0, v2, v0, -v107
	v_fma_f32 v1, v3, v1, v106
	v_add_f32_e32 v0, v0, v108
	v_add_f32_e32 v1, v1, v109
	v_cvt_pk_bf16_f32 v110, v0, v1
	ds_write_b32 v203, v110 offset:2048
	v_mul_f32_e32 v111, v84, v0
	v_mul_f32_e32 v112, v85, v1
	v_lshlrev_b32_e32 v113, 16, v99
	v_and_b32_e32 v114, 0xffff0000, v99
	v_fma_f32 v0, v2, v0, -v112
	v_fma_f32 v1, v3, v1, v111
	v_add_f32_e32 v0, v0, v113
	v_add_f32_e32 v1, v1, v114
	v_cvt_pk_bf16_f32 v115, v0, v1
	ds_write_b32 v204, v115 offset:2304
	v_mul_f32_e32 v106, v84, v0
	v_mul_f32_e32 v107, v85, v1
	v_lshlrev_b32_e32 v108, 16, v100
	v_and_b32_e32 v109, 0xffff0000, v100
	v_fma_f32 v0, v2, v0, -v107
	v_fma_f32 v1, v3, v1, v106
	v_add_f32_e32 v0, v0, v108
	v_add_f32_e32 v1, v1, v109
	v_cvt_pk_bf16_f32 v110, v0, v1
	ds_write_b32 v205, v110 offset:2560
	v_mul_f32_e32 v111, v84, v0
	v_mul_f32_e32 v112, v85, v1
	v_lshlrev_b32_e32 v113, 16, v101
	v_and_b32_e32 v114, 0xffff0000, v101
	v_fma_f32 v0, v2, v0, -v112
	v_fma_f32 v1, v3, v1, v111
	v_add_f32_e32 v0, v0, v113
	v_add_f32_e32 v1, v1, v114
	v_cvt_pk_bf16_f32 v115, v0, v1
	ds_write_b32 v206, v115 offset:2816
	v_mul_f32_e32 v106, v84, v0
	v_mul_f32_e32 v107, v85, v1
	v_lshlrev_b32_e32 v108, 16, v102
	v_and_b32_e32 v109, 0xffff0000, v102
	v_fma_f32 v0, v2, v0, -v107
	v_fma_f32 v1, v3, v1, v106
	v_add_f32_e32 v0, v0, v108
	v_add_f32_e32 v1, v1, v109
	v_cvt_pk_bf16_f32 v110, v0, v1
	ds_write_b32 v207, v110 offset:3072
	v_mul_f32_e32 v111, v84, v0
	v_mul_f32_e32 v112, v85, v1
	v_lshlrev_b32_e32 v113, 16, v103
	v_and_b32_e32 v114, 0xffff0000, v103
	v_fma_f32 v0, v2, v0, -v112
	v_fma_f32 v1, v3, v1, v111
	v_add_f32_e32 v0, v0, v113
	v_add_f32_e32 v1, v1, v114
	v_cvt_pk_bf16_f32 v115, v0, v1
	ds_write_b32 v208, v115 offset:3328
	v_mul_f32_e32 v106, v84, v0
	v_mul_f32_e32 v107, v85, v1
	v_lshlrev_b32_e32 v108, 16, v104
	v_and_b32_e32 v109, 0xffff0000, v104
	v_fma_f32 v0, v2, v0, -v107
	v_fma_f32 v1, v3, v1, v106
	v_add_f32_e32 v0, v0, v108
	v_add_f32_e32 v1, v1, v109
	v_cvt_pk_bf16_f32 v110, v0, v1
	ds_write_b32 v209, v110 offset:3584
	v_mul_f32_e32 v111, v84, v0
	v_mul_f32_e32 v112, v85, v1
	v_lshlrev_b32_e32 v113, 16, v105
	v_and_b32_e32 v114, 0xffff0000, v105
	v_fma_f32 v0, v2, v0, -v112
	v_fma_f32 v1, v3, v1, v111
	v_add_f32_e32 v0, v0, v113
	v_add_f32_e32 v1, v1, v114
	v_cvt_pk_bf16_f32 v115, v0, v1
	ds_write_b32 v210, v115 offset:3840
	s_waitcnt lgkmcnt(8)
	ds_read2st64_b32 v[98:99], v211 offset0:24 offset1:25
	ds_read2st64_b32 v[100:101], v211 offset0:26 offset1:27
	ds_read2st64_b32 v[102:103], v211 offset0:28 offset1:29
	ds_read2st64_b32 v[104:105], v211 offset0:30 offset1:31
	v_mul_f32_e32 v106, v84, v0
	v_mul_f32_e32 v107, v85, v1
	v_lshlrev_b32_e32 v108, 16, v52
	v_and_b32_e32 v109, 0xffff0000, v52
	v_fma_f32 v0, v2, v0, -v107
	v_fma_f32 v1, v3, v1, v106
	v_add_f32_e32 v0, v0, v108
	v_add_f32_e32 v1, v1, v109
	v_cvt_pk_bf16_f32 v110, v0, v1
	ds_write_b32 v195, v110 offset:4096
	v_mul_f32_e32 v111, v84, v0
	v_mul_f32_e32 v112, v85, v1
	v_lshlrev_b32_e32 v113, 16, v53
	v_and_b32_e32 v114, 0xffff0000, v53
	v_fma_f32 v0, v2, v0, -v112
	v_fma_f32 v1, v3, v1, v111
	v_add_f32_e32 v0, v0, v113
	v_add_f32_e32 v1, v1, v114
	v_cvt_pk_bf16_f32 v115, v0, v1
	ds_write_b32 v196, v115 offset:4352
	v_mul_f32_e32 v106, v84, v0
	v_mul_f32_e32 v107, v85, v1
	v_lshlrev_b32_e32 v108, 16, v54
	v_and_b32_e32 v109, 0xffff0000, v54
	v_fma_f32 v0, v2, v0, -v107
	v_fma_f32 v1, v3, v1, v106
	v_add_f32_e32 v0, v0, v108
	v_add_f32_e32 v1, v1, v109
	v_cvt_pk_bf16_f32 v110, v0, v1
	ds_write_b32 v197, v110 offset:4608
	v_mul_f32_e32 v111, v84, v0
	v_mul_f32_e32 v112, v85, v1
	v_lshlrev_b32_e32 v113, 16, v55
	v_and_b32_e32 v114, 0xffff0000, v55
	v_fma_f32 v0, v2, v0, -v112
	v_fma_f32 v1, v3, v1, v111
	v_add_f32_e32 v0, v0, v113
	v_add_f32_e32 v1, v1, v114
	v_cvt_pk_bf16_f32 v115, v0, v1
	ds_write_b32 v198, v115 offset:4864
	v_mul_f32_e32 v106, v84, v0
	v_mul_f32_e32 v107, v85, v1
	v_lshlrev_b32_e32 v108, 16, v56
	v_and_b32_e32 v109, 0xffff0000, v56
	v_fma_f32 v0, v2, v0, -v107
	v_fma_f32 v1, v3, v1, v106
	v_add_f32_e32 v0, v0, v108
	v_add_f32_e32 v1, v1, v109
	v_cvt_pk_bf16_f32 v110, v0, v1
	ds_write_b32 v199, v110 offset:5120
	v_mul_f32_e32 v111, v84, v0
	v_mul_f32_e32 v112, v85, v1
	v_lshlrev_b32_e32 v113, 16, v57
	v_and_b32_e32 v114, 0xffff0000, v57
	v_fma_f32 v0, v2, v0, -v112
	v_fma_f32 v1, v3, v1, v111
	v_add_f32_e32 v0, v0, v113
	v_add_f32_e32 v1, v1, v114
	v_cvt_pk_bf16_f32 v115, v0, v1
	ds_write_b32 v200, v115 offset:5376
	v_mul_f32_e32 v106, v84, v0
	v_mul_f32_e32 v107, v85, v1
	v_lshlrev_b32_e32 v108, 16, v58
	v_and_b32_e32 v109, 0xffff0000, v58
	v_fma_f32 v0, v2, v0, -v107
	v_fma_f32 v1, v3, v1, v106
	v_add_f32_e32 v0, v0, v108
	v_add_f32_e32 v1, v1, v109
	v_cvt_pk_bf16_f32 v110, v0, v1
	ds_write_b32 v201, v110 offset:5632
	v_mul_f32_e32 v111, v84, v0
	v_mul_f32_e32 v112, v85, v1
	v_lshlrev_b32_e32 v113, 16, v59
	v_and_b32_e32 v114, 0xffff0000, v59
	v_fma_f32 v0, v2, v0, -v112
	v_fma_f32 v1, v3, v1, v111
	v_add_f32_e32 v0, v0, v113
	v_add_f32_e32 v1, v1, v114
	v_cvt_pk_bf16_f32 v115, v0, v1
	ds_write_b32 v202, v115 offset:5888
	s_waitcnt lgkmcnt(8)
; #define LAS __attribute__((address_space(3)))
; __device__ __forceinline__ unsigned f2bf(float f) { unsigned u = __builtin_bit_cast(unsigned, f); return (u + 0x7fffu + ((u >> 16) & 1u)) >> 16; }
; __device__ __forceinline__ unsigned pk2(float lo, float hi) { const f32x2 v = {lo, hi}; const bf16x2_t b = __builtin_convertvector(v, bf16x2_t); return __builtin_bit_cast(unsigned, b); }
; __device__ __forceinline__ float gelu_tanh(float v) { const float z = 0.7978845608028654f * (v + 0.044715f * v * v * v); return v * (1.0f - 1.0f / (1.0f + __expf(2.0f * z))); }
; #define CBAR() asm volatile("s_waitcnt lgkmcnt(0)" ::: "memory")
; template <int PASS> __device__ __forceinline__ void ssm_phase(int j, LAS unsigned char* lds, int lane, int wave) { KARGS;
;     ...
;                 for (int l8 = 0; l8 < 32; l8 += 8) {
;                     unsigned w[8];
; #pragma unroll
;                     for (int q = 0; q < 8; ++q) w[q] = *(const LAS unsigned*)(buL + (l8 + q) * 256 + 4 * p);
; #pragma unroll
;                     for (int q = 0; q < 8; ++q) {
;                         const float nr = abr * hr - abi * hi + bflo(w[q]), ni = abr * hi + abi * hr + bfhi(w[q]); hr = nr; hi = ni;
;                         if (PASS == 3) *(LAS unsigned*)(hL + (l8 + q) * 256 + ((((p >> 2) ^ ((l8 + q) & 15))) << 4) + (p & 3) * 4) = pk2(hr, hi);
;                     }
;                 }
;                 CBAR();
;                 if (PASS == 3) {
; #pragma unroll
;                     for (int lt = 0; lt < 2; ++lt) {
;                         f32x4 y = {0.f, 0.f, 0.f, 0.f};
; #pragma unroll
;                         for (int ks = 0; ks < 4; ++ks) { const bf16x8 hf = *(const LAS bf16x8*)(hL + (16 * lt + fr) * 256 + (((4 * ks + fq) ^ fr) << 4)); y = __builtin_amdgcn_mfma_f32_16x16x32_bf16(hf, cf[ks], y, 0, 0, 0); }
;                         asm volatile("s_nop 15\n\ts_nop 15" : "+v"(y));
;                         const int ch = 16 * g + fr;
; #pragma unroll
;                         for (int r = 0; r < 4; ++r) { const int l = 32 * half + 16 * lt + 4 * fq + r; const size_t t = (size_t)(64 * c + l);
;                             const float v = y[r] + dd * X[t * D + ch] * rsL[l];
;                             GL[t * D + ch] = (bf16_t)f2bf(gelu_tanh(v)); }
	v_mul_f32_e32 v106, v84, v0
	v_mul_f32_e32 v107, v85, v1
	v_lshlrev_b32_e32 v108, 16, v98
	v_and_b32_e32 v109, 0xffff0000, v98
	v_fma_f32 v0, v2, v0, -v107
	v_fma_f32 v1, v3, v1, v106
	v_add_f32_e32 v0, v0, v108
	v_add_f32_e32 v1, v1, v109
	v_cvt_pk_bf16_f32 v110, v0, v1
	ds_write_b32 v203, v110 offset:6144
	v_mul_f32_e32 v111, v84, v0
	v_mul_f32_e32 v112, v85, v1
	v_lshlrev_b32_e32 v113, 16, v99
	v_and_b32_e32 v114, 0xffff0000, v99
	v_fma_f32 v0, v2, v0, -v112
	v_fma_f32 v1, v3, v1, v111
	v_add_f32_e32 v0, v0, v113
	v_add_f32_e32 v1, v1, v114
	v_cvt_pk_bf16_f32 v115, v0, v1
	ds_write_b32 v204, v115 offset:6400
	v_mul_f32_e32 v106, v84, v0
	v_mul_f32_e32 v107, v85, v1
	v_lshlrev_b32_e32 v108, 16, v100
	v_and_b32_e32 v109, 0xffff0000, v100
	v_fma_f32 v0, v2, v0, -v107
	v_fma_f32 v1, v3, v1, v106
	v_add_f32_e32 v0, v0, v108
	v_add_f32_e32 v1, v1, v109
	v_cvt_pk_bf16_f32 v110, v0, v1
	ds_write_b32 v205, v110 offset:6656
	v_mul_f32_e32 v111, v84, v0
	v_mul_f32_e32 v112, v85, v1
	v_lshlrev_b32_e32 v113, 16, v101
	v_and_b32_e32 v114, 0xffff0000, v101
	v_fma_f32 v0, v2, v0, -v112
	v_fma_f32 v1, v3, v1, v111
	v_add_f32_e32 v0, v0, v113
	v_add_f32_e32 v1, v1, v114
	v_cvt_pk_bf16_f32 v115, v0, v1
	ds_write_b32 v206, v115 offset:6912
	v_mul_f32_e32 v106, v84, v0
	v_mul_f32_e32 v107, v85, v1
	v_lshlrev_b32_e32 v108, 16, v102
	v_and_b32_e32 v109, 0xffff0000, v102
	v_fma_f32 v0, v2, v0, -v107
	v_fma_f32 v1, v3, v1, v106
	v_add_f32_e32 v0, v0, v108
	v_add_f32_e32 v1, v1, v109
	v_cvt_pk_bf16_f32 v110, v0, v1
	ds_write_b32 v207, v110 offset:7168
	v_mul_f32_e32 v111, v84, v0
	v_mul_f32_e32 v112, v85, v1
	v_lshlrev_b32_e32 v113, 16, v103
	v_and_b32_e32 v114, 0xffff0000, v103
	v_fma_f32 v0, v2, v0, -v112
	v_fma_f32 v1, v3, v1, v111
	v_add_f32_e32 v0, v0, v113
	v_add_f32_e32 v1, v1, v114
	v_cvt_pk_bf16_f32 v115, v0, v1
	ds_write_b32 v208, v115 offset:7424
	v_mul_f32_e32 v106, v84, v0
	v_mul_f32_e32 v107, v85, v1
	v_lshlrev_b32_e32 v108, 16, v104
	v_and_b32_e32 v109, 0xffff0000, v104
	v_fma_f32 v0, v2, v0, -v107
	v_fma_f32 v1, v3, v1, v106
	v_add_f32_e32 v0, v0, v108
	v_add_f32_e32 v1, v1, v109
	v_cvt_pk_bf16_f32 v110, v0, v1
	ds_write_b32 v209, v110 offset:7680
	v_mul_f32_e32 v111, v84, v0
	v_mul_f32_e32 v112, v85, v1
	v_lshlrev_b32_e32 v113, 16, v105
	v_and_b32_e32 v114, 0xffff0000, v105
	v_fma_f32 v0, v2, v0, -v112
	v_fma_f32 v1, v3, v1, v111
	v_add_f32_e32 v0, v0, v113
	v_add_f32_e32 v1, v1, v114
	v_cvt_pk_bf16_f32 v115, v0, v1
	ds_write_b32 v210, v115 offset:7936
	s_waitcnt lgkmcnt(0)
	ds_read_b128 v[52:55], v87
	ds_read_b128 v[56:59], v92
	v_or_b32_e32 v97, s70, v72
	v_lshl_add_u32 v98, v97, 2, s18
	s_mov_b32 s70, 32
	s_waitcnt lgkmcnt(1)
	v_mfma_f32_16x16x32_bf16 v[52:55], v[52:55], v[36:39], 0
	s_waitcnt lgkmcnt(0)
	v_mfma_f32_16x16x32_bf16 v[52:55], v[56:59], v[40:43], v[52:55]
	ds_read_b128 v[56:59], v93
	s_waitcnt lgkmcnt(0)
	v_mfma_f32_16x16x32_bf16 v[52:55], v[56:59], v[44:47], v[52:55]
	ds_read_b128 v[56:59], v94
	s_waitcnt lgkmcnt(0)
	v_mfma_f32_16x16x32_bf16 v[52:55], v[56:59], v[48:51], v[52:55]
	v_or_b32_e32 v56, s12, v97
	v_ashrrev_i32_e32 v57, 31, v56
	v_lshlrev_b64 v[100:101], 11, v[56:57]
	v_or_b32_e32 v100, v100, v86
	v_lshl_add_u64 v[56:57], v[100:101], 2, s[60:61]
	s_nop 15
	s_nop 15
	v_lshl_add_u64 v[100:101], v[100:101], 1, s[64:65]
	s_waitcnt vmcnt(0)
	v_mul_f32_e32 v99, v83, v126
	ds_read_b128 v[56:59], v98 offset:16384
	s_waitcnt lgkmcnt(0)
	v_fma_f32 v52, v99, v56, v52
	v_mul_f32_e32 v56, 0x3d372713, v52
	v_mul_f32_e32 v56, v52, v56
	v_fma_f32 v56, v52, v56, v52
	v_mul_f32_e32 v56, 0x3f4c422a, v56
	v_add_f32_e32 v56, v56, v56
	v_mul_f32_e32 v56, 0x3fb8aa3b, v56
	v_exp_f32_e32 v56, v56
	s_nop 0
	v_add_f32_e32 v56, 1.0, v56
	v_div_scale_f32 v99, s[4:5], v56, v56, 1.0
	v_rcp_f32_e32 v102, v99
	s_nop 0
	v_fma_f32 v103, -v99, v102, 1.0
	v_fmac_f32_e32 v102, v103, v102
	v_div_scale_f32 v103, vcc, 1.0, v56, 1.0
	v_mul_f32_e32 v104, v103, v102
	v_fma_f32 v105, -v99, v104, v103
	v_fmac_f32_e32 v104, v105, v102
	v_fma_f32 v99, -v99, v104, v103
	v_div_fmas_f32 v99, v99, v102, v104
	v_div_fixup_f32 v56, v99, v56, 1.0
	v_sub_f32_e32 v56, 1.0, v56
	v_mul_f32_e32 v52, v52, v56
	v_bfe_u32 v56, v52, 16, 1
	v_add3_u32 v52, v52, v56, s75
	global_store_short_d16_hi v[100:101], v52, off
	v_or_b32_e32 v100, s54, v97
	v_ashrrev_i32_e32 v101, 31, v100
	v_lshlrev_b64 v[100:101], 11, v[100:101]
	v_or_b32_e32 v100, v100, v86
	v_lshl_add_u64 v[102:103], v[100:101], 2, s[60:61]
	v_mul_f32_e32 v52, v83, v127
	v_fma_f32 v52, v52, v57, v53
	v_mul_f32_e32 v53, 0x3d372713, v52
	v_mul_f32_e32 v53, v52, v53
	v_fma_f32 v53, v52, v53, v52
	v_mul_f32_e32 v53, 0x3f4c422a, v53
	v_add_f32_e32 v53, v53, v53
	v_mul_f32_e32 v53, 0x3fb8aa3b, v53
	v_exp_f32_e32 v53, v53
	s_nop 0
	v_add_f32_e32 v53, 1.0, v53
	v_div_scale_f32 v56, s[4:5], v53, v53, 1.0
	v_rcp_f32_e32 v57, v56
	s_nop 0
	v_fma_f32 v99, -v56, v57, 1.0
	v_fmac_f32_e32 v57, v99, v57
	v_div_scale_f32 v99, vcc, 1.0, v53, 1.0
	v_mul_f32_e32 v102, v99, v57
	v_fma_f32 v103, -v56, v102, v99
	v_fmac_f32_e32 v102, v103, v57
	v_fma_f32 v56, -v56, v102, v99
	v_div_fmas_f32 v56, v56, v57, v102
	v_div_fixup_f32 v53, v56, v53, 1.0
	v_sub_f32_e32 v53, 1.0, v53
	v_mul_f32_e32 v52, v52, v53
	v_bfe_u32 v53, v52, 16, 1
	v_add3_u32 v56, v52, v53, s75
	v_lshl_add_u64 v[52:53], v[100:101], 1, s[64:65]
	global_store_short_d16_hi v[52:53], v56, off
	v_or_b32_e32 v52, s55, v97
	v_ashrrev_i32_e32 v53, 31, v52
	v_lshlrev_b64 v[52:53], 11, v[52:53]
	v_or_b32_e32 v52, v52, v86
	v_lshl_add_u64 v[56:57], v[52:53], 2, s[60:61]
	v_lshl_add_u64 v[52:53], v[52:53], 1, s[64:65]
	v_mul_f32_e32 v56, v83, v128
	v_fma_f32 v54, v56, v58, v54
; #define LAS __attribute__((address_space(3)))
; __device__ __forceinline__ unsigned f2bf(float f) { unsigned u = __builtin_bit_cast(unsigned, f); return (u + 0x7fffu + ((u >> 16) & 1u)) >> 16; }
; __device__ __forceinline__ float gelu_tanh(float v) { const float z = 0.7978845608028654f * (v + 0.044715f * v * v * v); return v * (1.0f - 1.0f / (1.0f + __expf(2.0f * z))); }
; template <int PASS> __device__ __forceinline__ void ssm_phase(int j, LAS unsigned char* lds, int lane, int wave) { KARGS;
;     ...
;                         for (int ks = 0; ks < 4; ++ks) { const bf16x8 hf = *(const LAS bf16x8*)(hL + (16 * lt + fr) * 256 + (((4 * ks + fq) ^ fr) << 4)); y = __builtin_amdgcn_mfma_f32_16x16x32_bf16(hf, cf[ks], y, 0, 0, 0); }
;                         asm volatile("s_nop 15\n\ts_nop 15" : "+v"(y));
;                         const int ch = 16 * g + fr;
; #pragma unroll
;                         for (int r = 0; r < 4; ++r) { const int l = 32 * half + 16 * lt + 4 * fq + r; const size_t t = (size_t)(64 * c + l);
;                             const float v = y[r] + dd * X[t * D + ch] * rsL[l];
;                             GL[t * D + ch] = (bf16_t)f2bf(gelu_tanh(v)); }
	v_mul_f32_e32 v56, 0x3d372713, v54
	v_mul_f32_e32 v56, v54, v56
	v_fma_f32 v56, v54, v56, v54
	v_mul_f32_e32 v56, 0x3f4c422a, v56
	v_add_f32_e32 v56, v56, v56
	v_mul_f32_e32 v56, 0x3fb8aa3b, v56
	v_exp_f32_e32 v56, v56
	s_nop 0
	v_add_f32_e32 v56, 1.0, v56
	v_div_scale_f32 v57, s[4:5], v56, v56, 1.0
	v_rcp_f32_e32 v58, v57
	s_nop 0
	v_fma_f32 v99, -v57, v58, 1.0
	v_fmac_f32_e32 v58, v99, v58
	v_div_scale_f32 v99, vcc, 1.0, v56, 1.0
	v_mul_f32_e32 v100, v99, v58
	v_fma_f32 v101, -v57, v100, v99
	v_fmac_f32_e32 v100, v101, v58
	v_fma_f32 v57, -v57, v100, v99
	v_div_fmas_f32 v57, v57, v58, v100
	v_div_fixup_f32 v56, v57, v56, 1.0
	v_sub_f32_e32 v56, 1.0, v56
	v_mul_f32_e32 v54, v54, v56
	v_bfe_u32 v56, v54, 16, 1
	v_add3_u32 v54, v54, v56, s75
	global_store_short_d16_hi v[52:53], v54, off
	v_or_b32_e32 v52, s68, v97
	v_ashrrev_i32_e32 v53, 31, v52
	v_lshlrev_b64 v[52:53], 11, v[52:53]
	v_or_b32_e32 v52, v52, v86
	v_lshl_add_u64 v[56:57], v[52:53], 2, s[60:61]
	v_lshl_add_u64 v[52:53], v[52:53], 1, s[64:65]
	v_mul_f32_e32 v54, v83, v129
	v_fmac_f32_e32 v55, v54, v59
	v_mul_f32_e32 v54, 0x3d372713, v55
	v_mul_f32_e32 v54, v55, v54
	v_fma_f32 v54, v55, v54, v55
	v_mul_f32_e32 v54, 0x3f4c422a, v54
	v_add_f32_e32 v54, v54, v54
	v_mul_f32_e32 v54, 0x3fb8aa3b, v54
	v_exp_f32_e32 v54, v54
	s_nop 0
	v_add_f32_e32 v54, 1.0, v54
	v_div_scale_f32 v56, s[4:5], v54, v54, 1.0
	v_rcp_f32_e32 v57, v56
	s_nop 0
	v_fma_f32 v58, -v56, v57, 1.0
	v_fmac_f32_e32 v57, v58, v57
	v_div_scale_f32 v58, vcc, 1.0, v54, 1.0
	v_mul_f32_e32 v59, v58, v57
	v_fma_f32 v99, -v56, v59, v58
	v_fmac_f32_e32 v59, v99, v57
	v_fma_f32 v56, -v56, v59, v58
	v_div_fmas_f32 v56, v56, v57, v59
	v_div_fixup_f32 v54, v56, v54, 1.0
	v_sub_f32_e32 v54, 1.0, v54
	v_mul_f32_e32 v54, v55, v54
	v_bfe_u32 v55, v54, 16, 1
	v_add3_u32 v54, v54, v55, s75
	global_store_short_d16_hi v[52:53], v54, off
	ds_read_b128 v[52:55], v87 offset:4096
	ds_read_b128 v[56:59], v92 offset:4096
	s_waitcnt lgkmcnt(1)
	v_mfma_f32_16x16x32_bf16 v[52:55], v[52:55], v[36:39], 0
	s_waitcnt lgkmcnt(0)
	v_mfma_f32_16x16x32_bf16 v[52:55], v[56:59], v[40:43], v[52:55]
	ds_read_b128 v[56:59], v93 offset:4096
	s_waitcnt lgkmcnt(0)
	v_mfma_f32_16x16x32_bf16 v[52:55], v[56:59], v[44:47], v[52:55]
	ds_read_b128 v[56:59], v94 offset:4096
	s_waitcnt lgkmcnt(0)
	v_mfma_f32_16x16x32_bf16 v[52:55], v[56:59], v[48:51], v[52:55]
	v_or_b32_e32 v56, s13, v97
	v_ashrrev_i32_e32 v57, 31, v56
	v_lshlrev_b64 v[100:101], 11, v[56:57]
	v_or_b32_e32 v100, v100, v86
	v_lshl_add_u64 v[56:57], v[100:101], 2, s[60:61]
	s_nop 15
	s_nop 15
	v_mul_f32_e32 v99, v83, v130
	ds_read_b128 v[56:59], v98 offset:16448
	s_waitcnt lgkmcnt(0)
; #define LAS __attribute__((address_space(3)))
; __device__ __forceinline__ unsigned f2bf(float f) { unsigned u = __builtin_bit_cast(unsigned, f); return (u + 0x7fffu + ((u >> 16) & 1u)) >> 16; }
; __device__ __forceinline__ float gelu_tanh(float v) { const float z = 0.7978845608028654f * (v + 0.044715f * v * v * v); return v * (1.0f - 1.0f / (1.0f + __expf(2.0f * z))); }
; template <int PASS> __device__ __forceinline__ void ssm_phase(int j, LAS unsigned char* lds, int lane, int wave) { KARGS;
;     ...
;                     if (fq < 2) { const int l = 32 * half + 16 * lt + fr; const float rs = rsL[l]; const float* xp = X + (size_t)(64 * c + l) * D + 16 * g + 8 * fq;
;     ...
;                         for (int ks = 0; ks < 4; ++ks) { const bf16x8 hf = *(const LAS bf16x8*)(hL + (16 * lt + fr) * 256 + (((4 * ks + fq) ^ fr) << 4)); y = __builtin_amdgcn_mfma_f32_16x16x32_bf16(hf, cf[ks], y, 0, 0, 0); }
;                         asm volatile("s_nop 15\n\ts_nop 15" : "+v"(y));
;                         const int ch = 16 * g + fr;
; #pragma unroll
;                         for (int r = 0; r < 4; ++r) { const int l = 32 * half + 16 * lt + 4 * fq + r; const size_t t = (size_t)(64 * c + l);
;                             const float v = y[r] + dd * X[t * D + ch] * rsL[l];
;                             GL[t * D + ch] = (bf16_t)f2bf(gelu_tanh(v)); }
;                     }
	v_fma_f32 v52, v99, v56, v52
	v_mul_f32_e32 v56, 0x3d372713, v52
	v_mul_f32_e32 v56, v52, v56
	v_fma_f32 v56, v52, v56, v52
	v_mul_f32_e32 v56, 0x3f4c422a, v56
	v_add_f32_e32 v56, v56, v56
	v_mul_f32_e32 v56, 0x3fb8aa3b, v56
	v_exp_f32_e32 v56, v56
	s_nop 0
	v_add_f32_e32 v56, 1.0, v56
	v_div_scale_f32 v98, s[4:5], v56, v56, 1.0
	v_rcp_f32_e32 v99, v98
	s_nop 0
	v_fma_f32 v102, -v98, v99, 1.0
	v_fmac_f32_e32 v99, v102, v99
	v_div_scale_f32 v102, vcc, 1.0, v56, 1.0
	v_mul_f32_e32 v103, v102, v99
	v_fma_f32 v104, -v98, v103, v102
	v_fmac_f32_e32 v103, v104, v99
	v_fma_f32 v98, -v98, v103, v102
	v_div_fmas_f32 v98, v98, v99, v103
	v_div_fixup_f32 v56, v98, v56, 1.0
	v_sub_f32_e32 v56, 1.0, v56
	v_mul_f32_e32 v52, v52, v56
	v_bfe_u32 v56, v52, 16, 1
	v_add3_u32 v52, v52, v56, s75
	v_lshl_add_u64 v[98:99], v[100:101], 1, s[64:65]
	global_store_short_d16_hi v[98:99], v52, off
	v_or_b32_e32 v98, s77, v97
	v_ashrrev_i32_e32 v99, 31, v98
	v_lshlrev_b64 v[98:99], 11, v[98:99]
	v_or_b32_e32 v98, v98, v86
	v_lshl_add_u64 v[100:101], v[98:99], 2, s[60:61]
	v_mul_f32_e32 v52, v83, v131
	v_fma_f32 v52, v52, v57, v53
	v_mul_f32_e32 v53, 0x3d372713, v52
	v_mul_f32_e32 v53, v52, v53
	v_fma_f32 v53, v52, v53, v52
	v_mul_f32_e32 v53, 0x3f4c422a, v53
	v_add_f32_e32 v53, v53, v53
	v_mul_f32_e32 v53, 0x3fb8aa3b, v53
	v_exp_f32_e32 v53, v53
	s_nop 0
	v_add_f32_e32 v53, 1.0, v53
	v_div_scale_f32 v56, s[4:5], v53, v53, 1.0
	v_rcp_f32_e32 v57, v56
	s_nop 0
	v_fma_f32 v100, -v56, v57, 1.0
	v_fmac_f32_e32 v57, v100, v57
	v_div_scale_f32 v100, vcc, 1.0, v53, 1.0
	v_mul_f32_e32 v101, v100, v57
	v_fma_f32 v102, -v56, v101, v100
	v_fmac_f32_e32 v101, v102, v57
	v_fma_f32 v56, -v56, v101, v100
	v_div_fmas_f32 v56, v56, v57, v101
	v_div_fixup_f32 v53, v56, v53, 1.0
	v_sub_f32_e32 v53, 1.0, v53
	v_mul_f32_e32 v52, v52, v53
	v_bfe_u32 v53, v52, 16, 1
	v_add3_u32 v56, v52, v53, s75
	v_lshl_add_u64 v[52:53], v[98:99], 1, s[64:65]
	global_store_short_d16_hi v[52:53], v56, off
	v_or_b32_e32 v52, s80, v97
	v_ashrrev_i32_e32 v53, 31, v52
	v_lshlrev_b64 v[52:53], 11, v[52:53]
	v_or_b32_e32 v52, v52, v86
	v_lshl_add_u64 v[56:57], v[52:53], 2, s[60:61]
	v_lshl_add_u64 v[52:53], v[52:53], 1, s[64:65]
	v_mul_f32_e32 v56, v83, v132
	v_fma_f32 v54, v56, v58, v54
	v_mul_f32_e32 v56, 0x3d372713, v54
	v_mul_f32_e32 v56, v54, v56
	v_fma_f32 v56, v54, v56, v54
	v_mul_f32_e32 v56, 0x3f4c422a, v56
	v_add_f32_e32 v56, v56, v56
	v_mul_f32_e32 v56, 0x3fb8aa3b, v56
	v_exp_f32_e32 v56, v56
	s_nop 0
	v_add_f32_e32 v56, 1.0, v56
	v_div_scale_f32 v57, s[4:5], v56, v56, 1.0
	v_rcp_f32_e32 v58, v57
	s_nop 0
	v_fma_f32 v98, -v57, v58, 1.0
	v_fmac_f32_e32 v58, v98, v58
	v_div_scale_f32 v98, vcc, 1.0, v56, 1.0
	v_mul_f32_e32 v99, v98, v58
	v_fma_f32 v100, -v57, v99, v98
	v_fmac_f32_e32 v99, v100, v58
	v_fma_f32 v57, -v57, v99, v98
	v_div_fmas_f32 v57, v57, v58, v99
	v_div_fixup_f32 v56, v57, v56, 1.0
	v_sub_f32_e32 v56, 1.0, v56
	v_mul_f32_e32 v54, v54, v56
	v_bfe_u32 v56, v54, 16, 1
	v_add3_u32 v54, v54, v56, s75
	global_store_short_d16_hi v[52:53], v54, off
	v_or_b32_e32 v52, s81, v97
	v_ashrrev_i32_e32 v53, 31, v52
	v_lshlrev_b64 v[52:53], 11, v[52:53]
	v_or_b32_e32 v52, v52, v86
	v_lshl_add_u64 v[56:57], v[52:53], 2, s[60:61]
	v_lshl_add_u64 v[52:53], v[52:53], 1, s[64:65]
	v_mul_f32_e32 v54, v83, v133
	v_fmac_f32_e32 v55, v54, v59
	v_mul_f32_e32 v54, 0x3d372713, v55
	v_mul_f32_e32 v54, v55, v54
	v_fma_f32 v54, v55, v54, v55
	v_mul_f32_e32 v54, 0x3f4c422a, v54
	v_add_f32_e32 v54, v54, v54
	v_mul_f32_e32 v54, 0x3fb8aa3b, v54
	v_exp_f32_e32 v54, v54
	s_nop 0
	v_add_f32_e32 v54, 1.0, v54
	v_div_scale_f32 v56, s[4:5], v54, v54, 1.0
	v_rcp_f32_e32 v57, v56
	s_mov_b64 s[4:5], 0
	v_fma_f32 v58, -v56, v57, 1.0
	v_fmac_f32_e32 v57, v58, v57
	v_div_scale_f32 v58, vcc, 1.0, v54, 1.0
	v_mul_f32_e32 v59, v58, v57
	v_fma_f32 v97, -v56, v59, v58
	v_fmac_f32_e32 v59, v97, v57
	v_fma_f32 v56, -v56, v59, v58
	v_div_fmas_f32 v56, v56, v57, v59
	v_div_fixup_f32 v54, v56, v54, 1.0
	v_sub_f32_e32 v54, 1.0, v54
	v_mul_f32_e32 v54, v55, v54
	v_bfe_u32 v55, v54, 16, 1
	v_add3_u32 v54, v54, v55, s75
	global_store_short_d16_hi v[52:53], v54, off
	s_waitcnt lgkmcnt(0)
	v_mov_b64_e32 v[156:157], v[172:173]
	v_mov_b64_e32 v[158:159], v[174:175]
	v_mov_b64_e32 v[160:161], v[176:177]
	v_mov_b64_e32 v[162:163], v[178:179]
	v_mov_b64_e32 v[164:165], v[180:181]
	v_mov_b64_e32 v[166:167], v[182:183]
	v_mov_b64_e32 v[168:169], v[184:185]
	v_mov_b64_e32 v[170:171], v[186:187]
	s_and_b64 vcc, exec, s[10:11]
	s_cbranch_vccz .LBB0_343
	s_cmpk_lg_i32 s53, 0x7f
	s_cbranch_scc0 .LBB0_354
	s_cmpk_gt_i32 s53, 0x7f
	s_mov_b64 s[12:13], 0
	s_cbranch_scc1 .LBB0_355
	s_and_b64 vcc, exec, s[4:5]
	v_lshlrev_b32_e32 v192, 2, v60
	s_cbranch_vccnz .LBB0_356

; #define LAS __attribute__((address_space(3)))
; __global__ void __launch_bounds__(NTHREADS, 2) mega_fwd(Args a_unused) {
;     extern __shared__ __attribute__((aligned(16))) unsigned char lds_raw[];
;     LAS unsigned char* lds = (LAS unsigned char*)lds_raw;
	.amdhsa_kernel _Z8mega_fwd4Args
		.amdhsa_group_segment_fixed_size 0
		.amdhsa_private_segment_fixed_size 0
		.amdhsa_kernarg_size 488
		.amdhsa_user_sgpr_count 2
		.amdhsa_user_sgpr_dispatch_ptr 0
		.amdhsa_user_sgpr_queue_ptr 0
		.amdhsa_user_sgpr_kernarg_segment_ptr 1
		.amdhsa_user_sgpr_dispatch_id 0
		.amdhsa_user_sgpr_kernarg_preload_length 0
		.amdhsa_user_sgpr_kernarg_preload_offset 0
		.amdhsa_user_sgpr_private_segment_size 0
		.amdhsa_uses_dynamic_stack 0
		.amdhsa_enable_private_segment 0
		.amdhsa_system_sgpr_workgroup_id_x 1
		.amdhsa_system_sgpr_workgroup_id_y 0
		.amdhsa_system_sgpr_workgroup_id_z 0
		.amdhsa_system_sgpr_workgroup_info 0
		.amdhsa_system_vgpr_workitem_id 2
		.amdhsa_next_free_vgpr 256
		.amdhsa_next_free_sgpr 102
		.amdhsa_accum_offset 256
		.amdhsa_reserve_vcc 1
		.amdhsa_float_round_mode_32 0
		.amdhsa_float_round_mode_16_64 0
		.amdhsa_float_denorm_mode_32 3
		.amdhsa_float_denorm_mode_16_64 3
		.amdhsa_dx10_clamp 1
		.amdhsa_ieee_mode 1
		.amdhsa_fp16_overflow 0
		.amdhsa_tg_split 0
		.amdhsa_exception_fp_ieee_invalid_op 0
		.amdhsa_exception_fp_denorm_src 0
		.amdhsa_exception_fp_ieee_div_zero 0
		.amdhsa_exception_fp_ieee_overflow 0
		.amdhsa_exception_fp_ieee_underflow 0
		.amdhsa_exception_fp_ieee_inexact 0
		.amdhsa_exception_int_div_zero 0
	.end_amdhsa_kernel

; #define LAS __attribute__((address_space(3)))
; __global__ void __launch_bounds__(NTHREADS, 2) mega_fwd(Args a_unused) {
;     extern __shared__ __attribute__((aligned(16))) unsigned char lds_raw[];
;     LAS unsigned char* lds = (LAS unsigned char*)lds_raw;
amdhsa.kernels:
  - .agpr_count:     0
    .args:
      - .offset:         0
        .size:           232
        .value_kind:     by_value
      - .offset:         232
        .size:           4
        .value_kind:     hidden_block_count_x
      - .offset:         236
        .size:           4
        .value_kind:     hidden_block_count_y
      - .offset:         240
        .size:           4
        .value_kind:     hidden_block_count_z
      - .offset:         244
        .size:           2
        .value_kind:     hidden_group_size_x
      - .offset:         246
        .size:           2
        .value_kind:     hidden_group_size_y
      - .offset:         248
        .size:           2
        .value_kind:     hidden_group_size_z
      - .offset:         250
        .size:           2
        .value_kind:     hidden_remainder_x
      - .offset:         252
        .size:           2
        .value_kind:     hidden_remainder_y
      - .offset:         254
        .size:           2
        .value_kind:     hidden_remainder_z
      - .offset:         272
        .size:           8
        .value_kind:     hidden_global_offset_x
      - .offset:         280
        .size:           8
        .value_kind:     hidden_global_offset_y
      - .offset:         288
        .size:           8
        .value_kind:     hidden_global_offset_z
      - .offset:         296
        .size:           2
        .value_kind:     hidden_grid_dims
      - .offset:         320
        .size:           8
        .value_kind:     hidden_multigrid_sync_arg
      - .offset:         352
        .size:           4
        .value_kind:     hidden_dynamic_lds_size
    .group_segment_fixed_size: 0
    .kernarg_segment_align: 8
    .kernarg_segment_size: 488
    .language:       OpenCL C
    .language_version:
      - 2
      - 0
    .max_flat_workgroup_size: 512
    .name:           _Z8mega_fwd4Args
    .private_segment_fixed_size: 0
    .sgpr_count:     108
    .sgpr_spill_count: 58
    .symbol:         _Z8mega_fwd4Args.kd
    .uniform_work_group_size: 1
    .uses_dynamic_stack: false
    .vgpr_count:     256
    .vgpr_spill_count: 0
    .wavefront_size: 64
